# attention loop: wave roles swapped (waves 0-3 MFMA-then-softmax, waves 4-7 softmax-then-MFMA)
# speedup vs baseline: 1.0113x; 1.0113x over previous
; #define LAS __attribute__((address_space(3)))
; DI void attn_phase(const Params& p, const int layer, const int wid_s) {
;     ...
; #pragma unroll 1
;       for (int br = 1; br <= 2; ++br) {
;         const h16* kbase = hb + (br == 1 ? C_KS : C_KW) + g * 64;
;         const h16* vT = (const h16*)(p.ws + (br == 1 ? OFF_VST : OFF_VWT)) + (size_t)bg * 64 * SEQ;
;         int kb0 = 0, lo_w = 0;
;         if (br == 2) { kb0 = qblk * 64 - 512; if (kb0 < 0) kb0 = 0; lo_w = t0 - 511; if (lo_w < 0) lo_w = 0; lo_w &= ~31; }
;         const int nsteps = (kb_last - kb0) / 32 + 1;
;         f32x4 O[2][4]; float l[2];
; #pragma unroll
;         for (int hp = 0; hp < 2; ++hp) { l[hp] = 0.f;
; #pragma unroll
;           for (int dt = 0; dt < 4; ++dt) O[hp][dt] = (f32x4){0.f, 0.f, 0.f, 0.f}; }
;     ...
;         asm volatile("s_waitcnt vmcnt(0)" ::: "memory");
;         __syncthreads();
;         RING_ISSUE(0); RING_ISSUE(1);
; #pragma unroll 1
;         for (int si = 0; si < nsteps; ++si) {
;           asm volatile("s_waitcnt vmcnt(1) lgkmcnt(0)" ::: "memory");
;           __builtin_amdgcn_s_barrier();
;           asm volatile("" ::: "memory");
;           RING_ISSUE(si + 2);
;           const int kb = kb0 + si * 32;
;           if (kb > kmax_w || kb < lo_w) continue;
;           if (br == 1 && kb + 31 + 128 <= t0 && __ballot((selmask >> (kb >> 6)) & 1u) == 0ull) continue;
;           LAS unsigned char* slotp = ring + (si % 3) * 8192;
;           KF kv;
; #pragma unroll
;           for (int kt = 0; kt < 2; ++kt)
; #pragma unroll
;             for (int ks = 0; ks < 2; ++ks) kv.k[kt][ks] = *(const LAS half8*)(slotp + kread[kt][ks]);
; #pragma unroll
;           for (int dt = 0; dt < 4; ++dt) kv.v[dt] = *(const LAS half8*)(slotp + vread[dt]);
;           if (br == 1) {
;             const bool bit = (selmask >> (kb >> 6)) & 1u;
;             if (kb + 31 + 128 <= t0) attn_step<true, false>(kv, kb, t, lane, bit, tabh, q, O, nRs, l);
;             else attn_step<true, true>(kv, kb, t, lane, bit, tabh, q, O, nRs, l);
;           } else {
;             const bool gen = (kb + 31 + 128 > t0) || (kb + 512 <= t0 + 15);
;             if (!gen) attn_step<false, false>(kv, kb, t, lane, true, tabh, q, O, nRw, l);
;             else attn_step<false, true>(kv, kb, t, lane, true, tabh, q, O, nRw, l);
;           }
;         }
.LBB0_349:
	s_and_b64 vcc, exec, s[30:31]
	s_cbranch_vccz .Lat_ytop
	s_branch .Lat_xtop
